# stack + FFN-up unit start: dropped compiler vmcnt(0) drain in accumulator zeroing block
# speedup vs baseline: 1.0009x; 1.0009x over previous
.LBB0_166:
	s_ashr_i32 s27, s26, 31
	s_lshl_b64 s[28:29], s[26:27], 19
	s_add_u32 s28, s69, s28
	s_addc_u32 s29, s78, s29
	s_and_b64 s[30:31], s[4:5], exec
	s_cselect_b32 s2, s29, s39
	s_cselect_b32 s15, s28, s38
	s_ashr_i32 s25, s24, 31
	s_lshl_b64 s[30:31], s[24:25], 19
	s_add_u32 s30, s7, s30
	s_addc_u32 s31, s79, s31
	s_and_b64 s[42:43], s[4:5], exec
	s_cselect_b32 s25, s31, s63
	s_cselect_b32 s27, s30, s62
	s_add_u32 s38, s38, 0x40080
	s_addc_u32 s39, s39, 0
	s_add_u32 s35, s62, 0x100
	v_mov_b32_e32 v2, 0
	s_addc_u32 s42, s63, 0
	s_mov_b32 s43, -2
	v_mov_b32_e32 v3, v2
	v_mov_b32_e32 v4, v2
	v_mov_b32_e32 v5, v2
	v_mov_b32_e32 v10, v2
	v_mov_b32_e32 v11, v2
	v_mov_b32_e32 v12, v2
	v_mov_b32_e32 v13, v2
	v_mov_b32_e32 v18, v2
	v_mov_b32_e32 v19, v2
	v_mov_b32_e32 v20, v2
	v_mov_b32_e32 v21, v2
	v_mov_b32_e32 v26, v2
	v_mov_b32_e32 v27, v2
	v_mov_b32_e32 v28, v2
	v_mov_b32_e32 v29, v2
	v_mov_b32_e32 v34, v2
	v_mov_b32_e32 v35, v2
	v_mov_b32_e32 v36, v2
	v_mov_b32_e32 v37, v2
	v_mov_b32_e32 v42, v2
	v_mov_b32_e32 v43, v2
	v_mov_b32_e32 v44, v2
	v_mov_b32_e32 v45, v2
	v_mov_b32_e32 v50, v2
	v_mov_b32_e32 v51, v2
	v_mov_b32_e32 v52, v2
	v_mov_b32_e32 v53, v2
	v_mov_b32_e32 v58, v2
	v_mov_b32_e32 v59, v2
	v_mov_b32_e32 v60, v2
	v_mov_b32_e32 v61, v2
	v_mov_b32_e32 v6, v2
	v_mov_b32_e32 v7, v2
	v_mov_b32_e32 v8, v2
	v_mov_b32_e32 v9, v2
	v_mov_b32_e32 v14, v2
	v_mov_b32_e32 v15, v2
	v_mov_b32_e32 v16, v2
	v_mov_b32_e32 v17, v2
	v_mov_b32_e32 v22, v2
	v_mov_b32_e32 v23, v2
	v_mov_b32_e32 v24, v2
	v_mov_b32_e32 v25, v2
	v_mov_b32_e32 v30, v2
	v_mov_b32_e32 v31, v2
	v_mov_b32_e32 v32, v2
	v_mov_b32_e32 v33, v2
	v_mov_b32_e32 v38, v2
	v_mov_b32_e32 v39, v2
	v_mov_b32_e32 v40, v2
	v_mov_b32_e32 v41, v2
	v_mov_b32_e32 v46, v2
	v_mov_b32_e32 v47, v2
	v_mov_b32_e32 v48, v2
	v_mov_b32_e32 v49, v2
	v_mov_b32_e32 v54, v2
	v_mov_b32_e32 v55, v2
	v_mov_b32_e32 v56, v2
	v_mov_b32_e32 v57, v2
	v_mov_b32_e32 v62, v2
	v_mov_b32_e32 v63, v2
	v_mov_b32_e32 v64, v2
	v_mov_b32_e32 v65, v2
	v_mov_b32_e32 v66, v2
	v_mov_b32_e32 v67, v2
	v_mov_b32_e32 v68, v2
	v_mov_b32_e32 v69, v2
	v_mov_b32_e32 v74, v2
	v_mov_b32_e32 v75, v2
	v_mov_b32_e32 v76, v2
	v_mov_b32_e32 v77, v2
	v_mov_b32_e32 v82, v2
	v_mov_b32_e32 v83, v2
	v_mov_b32_e32 v84, v2
	v_mov_b32_e32 v85, v2
	v_mov_b32_e32 v90, v2
	v_mov_b32_e32 v91, v2
	v_mov_b32_e32 v92, v2
	v_mov_b32_e32 v93, v2
	v_mov_b32_e32 v98, v2
	v_mov_b32_e32 v99, v2
	v_mov_b32_e32 v100, v2
	v_mov_b32_e32 v101, v2
	v_mov_b32_e32 v106, v2
	v_mov_b32_e32 v107, v2
	v_mov_b32_e32 v108, v2
	v_mov_b32_e32 v109, v2
	v_mov_b32_e32 v114, v2
	v_mov_b32_e32 v115, v2
	v_mov_b32_e32 v116, v2
	v_mov_b32_e32 v117, v2
	v_mov_b32_e32 v122, v2
	v_mov_b32_e32 v123, v2
	v_mov_b32_e32 v124, v2
	v_mov_b32_e32 v125, v2
	v_mov_b32_e32 v70, v2
	v_mov_b32_e32 v71, v2
	v_mov_b32_e32 v72, v2
	v_mov_b32_e32 v73, v2
	v_mov_b32_e32 v78, v2
	v_mov_b32_e32 v79, v2
	v_mov_b32_e32 v80, v2
	v_mov_b32_e32 v81, v2
	v_mov_b32_e32 v86, v2
	v_mov_b32_e32 v87, v2
	v_mov_b32_e32 v88, v2
	v_mov_b32_e32 v89, v2
	v_mov_b32_e32 v94, v2
	v_mov_b32_e32 v95, v2
	v_mov_b32_e32 v96, v2
	v_mov_b32_e32 v97, v2
	v_mov_b32_e32 v102, v2
	v_mov_b32_e32 v103, v2
	v_mov_b32_e32 v104, v2
	v_mov_b32_e32 v105, v2
	v_mov_b32_e32 v110, v2
	v_mov_b32_e32 v111, v2
	v_mov_b32_e32 v112, v2
	v_mov_b32_e32 v113, v2
	v_mov_b32_e32 v118, v2
	v_mov_b32_e32 v119, v2
	v_mov_b32_e32 v120, v2
	v_mov_b32_e32 v121, v2
	v_mov_b32_e32 v126, v2
	v_mov_b32_e32 v127, v2
	v_mov_b32_e32 v128, v2
	v_mov_b32_e32 v129, v2
